# v60 plus split-phase use of the four remaining chip-wide barriers: arrive, run the next phase's memory-free setup, wait for the release right before the first memory access (one late wait per control-
# speedup vs baseline: 1.0071x; 1.0071x over previous
.Lgb4_1_follow:
	s_branch .LBB0_131
	v_mov_b32_e32 v2, 1
	s_mov_b32 s99, 0

.LBB0_131:
	s_or_b64 exec, exec, s[6:7]
	v_mov_b32_e32 v10, v0
	s_cmpk_lt_i32 s38, 0x1e0
	s_waitcnt lgkmcnt(0)
	s_cselect_b64 s[4:5], -1, 0
	s_cmpk_gt_i32 s38, 0x1df
	v_readfirstlane_b32 s0, v10
	s_cbranch_scc1 .LBB0_133
	s_ashr_i32 s1, s38, 31
	s_lshr_b32 s1, s1, 29
	s_add_i32 s1, s38, s1
	s_ashr_i32 s3, s1, 3
	s_and_b32 s1, s1, -8
	s_sub_i32 s1, s38, s1
	s_cmp_lt_i32 s1, 0
	s_cselect_b32 s6, 61, 60
	s_mul_i32 s1, s1, s6
	s_add_i32 s1, s1, s3
	s_mul_hi_i32 s3, s1, 0x88888889
	s_add_i32 s3, s3, s1
	s_lshr_b32 s6, s3, 31
	s_ashr_i32 s3, s3, 5
	s_add_i32 s3, s3, s6
	s_mul_i32 s6, s3, 6
	s_mul_i32 s3, s3, 60
	s_sub_i32 s1, s1, s3
	s_bfe_i32 s3, s1, 0x80000
	s_mul_i32 s3, s3, 43
	s_bfe_u32 s7, s3, 0x1000f
	s_bfe_u32 s3, s3, 0x80008
	s_add_i32 s3, s3, s7
	s_mul_i32 s7, s3, 6
	s_sub_i32 s1, s1, s7
	s_sext_i32_i8 s1, s1
	s_add_i32 s70, s6, s1
	s_sext_i32_i8 s8, s3
.LBB0_133:
	s_add_u32 s20, s54, 0xe800000
	s_addc_u32 s21, s55, 0
	s_add_u32 s68, s54, 0x6400000
	s_addc_u32 s69, s55, 0
	s_andn2_b64 vcc, exec, s[4:5]
	s_cbranch_vccz .Lh1b_main
	v_readfirstlane_b32 s98, v0
	s_cmp_gt_u32 s98, 63
	s_cbranch_scc1 .Lh1b_done
	s_getreg_b32 s98, hwreg(HW_REG_XCC_ID, 0, 4)
	s_lshl_b32 s98, s98, 8
	v_mov_b32_e32 v230, s98
	v_add_u32_e32 v230, 0x6400, v230
	s_mov_b32 s98, 0
.Lh1b_spin:
	global_load_dword v231, v230, s[54:55] sc1
	s_waitcnt vmcnt(0)
	v_readfirstlane_b32 s99, v231
	s_cmp_ge_u32 s99, 1
	s_cbranch_scc1 .Lh1b_done
	s_add_i32 s98, s98, 1
	s_cmp_gt_u32 s98, 0x40000
	s_cbranch_scc1 .Lh1b_done
	s_sleep 1
	s_branch .Lh1b_spin
.Lh1b_done:
	s_barrier
	s_branch .LBB0_213
.Lh1b_main:
	v_ashrrev_i32_e32 v2, 31, v10
	v_lshrrev_b32_e32 v2, 26, v2
	v_add_u32_e32 v2, v10, v2
	v_ashrrev_i32_e32 v11, 6, v2
	v_bfe_i32 v2, v10, 27, 1
	v_lshlrev_b32_e32 v1, 4, v10
	v_lshrrev_b32_e32 v2, 22, v2
	v_add_u32_e32 v2, v1, v2
	v_and_b32_e32 v2, 0xfffffc00, v2
	v_sub_u32_e32 v2, v1, v2
	v_lshrrev_b32_e32 v3, 4, v2
	v_bitop3_b32 v2, v3, v2, 32 bitop3:0x6c
	v_ashrrev_i32_e32 v4, 31, v2
	v_lshrrev_b32_e32 v4, 26, v4
	v_add_u32_e32 v4, v2, v4
	v_lshlrev_b32_e32 v3, 3, v11
	v_ashrrev_i32_e32 v12, 6, v4
	v_and_b32_e32 v4, 0xc0, v4
	v_and_b32_e32 v3, -16, v3
	v_sub_u32_e32 v2, v2, v4
	v_mov_b32_e32 v4, 1
	v_add_u32_e32 v3, v12, v3
	v_ashrrev_i16_sdwa v2, v4, sext(v2) dst_sel:DWORD dst_unused:UNUSED_PAD src0_sel:DWORD src1_sel:BYTE_0
	v_lshlrev_b32_e32 v5, 5, v11
	v_bfe_i32 v13, v2, 0, 16
	v_lshlrev_b32_e32 v2, 1, v3
	v_lshrrev_b32_e32 v6, 2, v3
	v_and_b32_e32 v7, 3, v12
	s_mov_b32 s3, 0x1fffe0
	v_and_b32_e32 v5, 32, v5
	v_and_b32_e32 v2, 24, v2
	v_and_b32_e32 v6, 4, v6
	v_and_or_b32 v7, v3, s3, v7
	v_or3_b32 v2, v7, v6, v2
	v_add_lshl_u32 v5, v5, v13, 1
	v_add_u32_e32 v1, 0x2000, v1
	v_lshl_add_u32 v132, v2, 11, v5
	v_ashrrev_i32_e32 v2, 31, v1
	v_lshrrev_b32_e32 v2, 22, v2
	v_add_u32_e32 v2, v1, v2
	v_ashrrev_i32_e32 v14, 10, v2
	v_mul_i32_i24_e32 v2, 0x400, v14
	v_sub_u32_e32 v1, v1, v2
	v_lshrrev_b32_e32 v2, 4, v1
	v_bitop3_b32 v1, v2, v1, 32 bitop3:0x6c
	v_lshl_add_u32 v130, v3, 11, v5
	v_ashrrev_i32_e32 v3, 31, v1
	v_lshrrev_b32_e32 v3, 26, v3
	v_add_u32_e32 v3, v1, v3
	v_lshlrev_b32_e32 v2, 3, v14
	v_ashrrev_i32_e32 v15, 6, v3
	v_and_b32_e32 v3, 0xc0, v3
	v_and_b32_e32 v2, -16, v2
	v_sub_u32_e32 v1, v1, v3
	v_add_u32_e32 v2, v15, v2
	v_ashrrev_i16_sdwa v1, v4, sext(v1) dst_sel:DWORD dst_unused:UNUSED_PAD src0_sel:DWORD src1_sel:BYTE_0
	v_and_b32_e32 v4, 3, v15
	s_ashr_i32 s4, s0, 6
	s_ashr_i32 s71, s70, 31
	s_ashr_i32 s9, s8, 31
	s_ashr_i32 s1, s0, 8
	v_and_or_b32 v4, v2, s3, v4
	s_lshl_b32 s3, s4, 10
	s_lshl_b64 s[6:7], s[70:71], 19
	s_lshl_b64 s[10:11], s[8:9], 19
	s_add_u32 s74, s18, s10
	v_lshlrev_b32_e32 v5, 5, v14
	v_bfe_i32 v16, v1, 0, 16
	v_lshlrev_b32_e32 v1, 1, v2
	v_lshrrev_b32_e32 v3, 2, v2
	s_addc_u32 s75, s19, s11
	s_add_i32 s13, s3, 0
	v_and_b32_e32 v5, 32, v5
	v_and_b32_e32 v1, 24, v1
	v_and_b32_e32 v3, 4, v3
	s_add_i32 m0, s13, 0x10000
	v_or3_b32 v1, v4, v3, v1
	v_add_lshl_u32 v3, v5, v16, 1
	v_readfirstlane_b32 s98, v0
	s_cmp_gt_u32 s98, 63
	s_cbranch_scc1 .Lh1a_done
	s_getreg_b32 s98, hwreg(HW_REG_XCC_ID, 0, 4)
	s_lshl_b32 s98, s98, 8
	v_mov_b32_e32 v230, s98
	v_add_u32_e32 v230, 0x6400, v230
	s_mov_b32 s98, 0

.Lh1a_done:
	s_barrier
	global_load_lds_dwordx4 v132, s[74:75]
	s_add_i32 m0, s13, 0x12000
	v_lshl_add_u32 v136, v1, 11, v3
	s_add_u32 s10, s74, 0x40000
	global_load_lds_dwordx4 v136, s[74:75]
	s_addc_u32 s11, s75, 0
	s_add_i32 m0, s13, 0x14000
	v_lshl_add_u32 v134, v2, 11, v3
	global_load_lds_dwordx4 v132, s[10:11]
	s_add_i32 m0, s13, 0x16000
	s_add_u32 s72, s66, s6
	s_addc_u32 s73, s67, s7
	s_add_i32 s78, s13, 0x2000
	global_load_lds_dwordx4 v136, s[10:11]
	s_mov_b32 m0, s13
	s_add_u32 s6, s72, 0x40000
	global_load_lds_dwordx4 v130, s[72:73]
	s_mov_b32 m0, s78
	s_addc_u32 s7, s73, 0
	s_add_i32 s79, s13, 0x4000
	global_load_lds_dwordx4 v134, s[72:73]
	s_mov_b32 m0, s79
	s_add_i32 s92, s13, 0x6000
	global_load_lds_dwordx4 v130, s[6:7]
	s_mov_b32 m0, s92
	v_mov_b32_e32 v133, 0
	global_load_lds_dwordx4 v134, s[6:7]
	v_mov_b32_e32 v137, v133
	v_mov_b32_e32 v131, v133
	v_mov_b32_e32 v135, v133
	s_cmp_eq_u32 s1, 1
	s_mov_b32 s2, s91
	s_mov_b64 s[14:15], s[96:97]
	s_mov_b32 s93, 0
	v_lshl_add_u64 v[8:9], s[74:75], 0, v[132:133]
	v_lshl_add_u64 v[6:7], s[74:75], 0, v[136:137]
	v_lshl_add_u64 v[2:3], s[72:73], 0, v[130:131]
	s_cselect_b64 s[22:23], -1, 0
	s_cmp_lg_u32 s1, 1
	v_lshl_add_u64 v[4:5], s[72:73], 0, v[134:135]
	s_cbranch_scc1 .LBB0_136
	s_barrier

.Lgb4_2_follow:
	s_branch .LBB0_272
	v_mov_b32_e32 v2, 2
	s_mov_b32 s99, 0

.LBB0_272:
	s_or_b64 exec, exec, s[6:7]
	s_add_u32 s92, s54, 0xa000000
	s_addc_u32 s93, s55, 0
	s_add_u32 s82, s54, 0x2400
	s_addc_u32 s83, s55, 0
	s_add_u32 s80, s54, 0xd000000
	v_mov_b32_e32 v130, v0
	s_addc_u32 s81, s55, 0
	s_waitcnt lgkmcnt(0)
	s_mov_b64 s[4:5], -1
	s_andn2_b64 vcc, exec, s[16:17]
	v_bfe_u32 v88, v130, 4, 2
	v_and_b32_e32 v135, 15, v130
	v_lshlrev_b32_e32 v89, 4, v130
	v_ashrrev_i32_e32 v1, 4, v130
	v_lshlrev_b32_e32 v141, 2, v130
	v_cmp_eq_u32_e64 s[34:35], 0, v130
	s_cbranch_vccnz .LBB0_279
	v_add_u32_e32 v4, 0x200, v130
	v_and_b32_e32 v66, 0xf0, v89
	v_ashrrev_i32_e32 v90, 4, v4
	v_add_u32_e32 v4, 0x400, v130
	s_add_i32 s0, 0, 0x11000
	v_and_b32_e32 v7, 12, v141
	v_ashrrev_i32_e32 v91, 4, v4
	v_add_u32_e32 v4, 0x600, v130
	v_add_u32_e32 v5, s0, v66
	v_lshlrev_b32_e32 v93, 1, v7
	v_sub_u32_e32 v7, 0xff, v1
	s_movk_i32 s0, 0x110
	v_ashrrev_i32_e32 v92, 4, v4
	v_add_u32_e32 v4, 0, v66
	v_cvt_f32_i32_e32 v94, v7
	v_mul_lo_u32 v7, v1, s0
	v_add_u32_e32 v96, v4, v7
	v_add_u32_e32 v97, v5, v7
	v_sub_u32_e32 v7, 0xff, v90
	v_cvt_f32_i32_e32 v98, v7
	v_mul_lo_u32 v7, v90, s0
	v_add_u32_e32 v100, v4, v7
	v_add_u32_e32 v101, v5, v7
	v_sub_u32_e32 v7, 0xff, v91
	v_cvt_f32_i32_e32 v102, v7
	v_mul_lo_u32 v7, v91, s0
	v_add_u32_e32 v104, v4, v7
	v_add_u32_e32 v105, v5, v7
	v_sub_u32_e32 v7, 0xff, v92
	v_cvt_f32_i32_e32 v106, v7
	v_mul_lo_u32 v7, v92, s0
	v_add_u32_e32 v108, v4, v7
	v_add_u32_e32 v109, v5, v7
	v_add_u32_e32 v4, 0x80, v1
	v_sub_u32_e32 v5, 0x7f, v1
	v_cvt_f32_i32_e32 v112, v5
	v_cvt_f32_i32_e32 v113, v4
	v_add_u32_e32 v4, 0x80, v90
	v_sub_u32_e32 v5, 0x7f, v90
	s_lshl_b32 s3, s38, 1
	v_cvt_f32_i32_e32 v114, v5
	v_cvt_f32_i32_e32 v115, v4
	v_add_u32_e32 v4, 0x80, v91
	v_sub_u32_e32 v5, 0x7f, v91
	s_add_i32 s36, s3, 0xfffffec0
	v_cvt_f32_i32_e32 v116, v5
	v_cvt_f32_i32_e32 v117, v4
	v_add_u32_e32 v4, 0x80, v92
	v_sub_u32_e32 v5, 0x7f, v92
	s_bfe_u32 s18, s38, 0x20002
	v_readlane_b32 s0, v242, 0
	v_bfe_u32 v6, v130, 2, 2
	v_cvt_f32_i32_e32 v95, v1
	v_cvt_f32_i32_e32 v99, v90
	v_cvt_f32_i32_e32 v103, v91
	v_cvt_f32_i32_e32 v107, v92
	v_cvt_f32_i32_e32 v118, v5
	v_cvt_f32_i32_e32 v119, v4
	s_lshl_b32 s16, s18, 2
	v_readlane_b32 s4, v242, 4
	v_mov_b32_e32 v67, 0
	v_lshl_or_b32 v6, v88, 3, v6
	v_lshlrev_b32_e32 v4, 7, v135
	v_readlane_b32 s5, v242, 5
	s_add_u32 s16, s4, s16
	s_mov_b32 s73, 0
	v_lshl_add_u64 v[2:3], s[68:69], 0, v[66:67]
	v_mul_u32_u24_e32 v110, 0x110, v6
	v_lshlrev_b32_e32 v6, 2, v88
	v_or_b32_e32 v8, 0x800, v4
	v_or_b32_e32 v10, 0x1000, v4
	v_or_b32_e32 v12, 0x1800, v4
	v_or_b32_e32 v14, 0x2000, v4
	v_or_b32_e32 v16, 0x2800, v4
	v_or_b32_e32 v18, 0x3000, v4
	v_or_b32_e32 v20, 0x3800, v4
	v_readlane_b32 s1, v242, 1
	v_readlane_b32 s10, v242, 10
	v_readlane_b32 s11, v242, 11
	s_addc_u32 s17, s5, 0
	s_lshl_b32 s72, s18, 8
	v_add3_u32 v111, 0, v93, v110
	v_lshl_add_u64 v[68:69], v[2:3], 0, s[72:73]
	s_mov_b64 s[18:19], -1
	s_mov_b32 s0, 0xbfb8aa3b
	s_mov_b32 s1, 0x42ce8ed0
	s_mov_b32 s10, 0xc2b17218
	s_mov_b32 s11, 0x7f800000
	s_mov_b32 s24, 0x3f2aaaab
	v_mov_b32_e32 v120, 0x3ecc95a3
	s_mov_b32 s25, 0x3f317218
	s_mov_b32 s26, 0x33800000
	s_movk_i32 s27, 0x1400
	s_mov_b32 s28, 0x8800
	v_lshlrev_b32_e32 v70, 1, v6
	v_lshlrev_b32_e32 v72, 1, v4
	v_lshlrev_b32_e32 v74, 1, v8
	v_lshlrev_b32_e32 v76, 1, v10
	v_lshlrev_b32_e32 v66, 1, v12
	v_lshlrev_b32_e32 v78, 1, v14
	v_lshlrev_b32_e32 v80, 1, v16
	v_lshlrev_b32_e32 v82, 1, v18
	v_lshlrev_b32_e32 v84, 1, v20
	v_mov_b32_e32 v121, 0x7f800000
	v_mov_b32_e32 v86, 0x3f317218
	v_mov_b32_e32 v71, v67
	v_mov_b32_e32 v73, v67
	v_mov_b32_e32 v75, v67
	v_mov_b32_e32 v77, v67
	s_mov_b32 s5, 0
	v_readlane_b32 s2, v242, 2
	v_readlane_b32 s3, v242, 3
	v_readlane_b32 s6, v242, 6
	v_readlane_b32 s7, v242, 7
	v_readlane_b32 s8, v242, 8
	v_readlane_b32 s9, v242, 9
	v_readlane_b32 s12, v242, 12
	v_readlane_b32 s13, v242, 13
	v_readlane_b32 s14, v242, 14
	v_readlane_b32 s15, v242, 15
	v_readfirstlane_b32 s98, v0
	s_cmp_gt_u32 s98, 63
	s_cbranch_scc1 .Lh2a_done
	s_getreg_b32 s98, hwreg(HW_REG_XCC_ID, 0, 4)
	s_lshl_b32 s98, s98, 8
	v_mov_b32_e32 v232, s98
	v_add_u32_e32 v232, 0x6400, v232
	s_mov_b32 s98, 0
.Lh2a_spin:
	global_load_dword v233, v232, s[54:55] sc1
	s_waitcnt vmcnt(0)
	v_readfirstlane_b32 s99, v233
	s_cmp_ge_u32 s99, 2
	s_cbranch_scc1 .Lh2a_done
	s_add_i32 s98, s98, 1
	s_cmp_gt_u32 s98, 0x40000
	s_cbranch_scc1 .Lh2a_done
	s_sleep 1
	s_branch .Lh2a_spin

.LBB0_279:
	s_and_b64 vcc, exec, s[4:5]
	s_cbranch_vccz .LBB0_291
	v_readfirstlane_b32 s98, v0
	s_cmp_gt_u32 s98, 63
	s_cbranch_scc1 .Lh2b_done
	s_getreg_b32 s98, hwreg(HW_REG_XCC_ID, 0, 4)
	s_lshl_b32 s98, s98, 8
	v_mov_b32_e32 v232, s98
	v_add_u32_e32 v232, 0x6400, v232
	s_mov_b32 s98, 0

.Lh2b_done:
	s_barrier
	s_ashr_i32 s1, s38, 3
	s_mul_hi_i32 s3, s1, 0x2aaaaaab
	s_lshl_b32 s0, s38, 2
	s_lshr_b32 s4, s3, 31
	s_and_b32 s0, s0, 28
	s_add_i32 s3, s3, s4
	s_add_i32 s0, s0, s3
	s_mul_i32 s3, s3, 6
	s_mul_i32 s0, s0, 6
	s_sub_i32 s1, s1, s3
	s_add_i32 s0, s0, s1
	s_mul_hi_i32 s3, s0, 0x2aaaaaab
	s_lshr_b32 s5, s3, 31
	s_add_i32 s6, s3, s5
	v_readfirstlane_b32 s4, v130
	s_mul_i32 s3, s6, -6
	s_ashr_i32 s1, s4, 6
	s_add_i32 s3, s3, s0
	s_cmp_gt_i32 s3, 1
	s_cselect_b64 s[16:17], -1, 0
	s_lshl_b32 s18, s1, 5
	s_ashr_i32 s7, s6, 31
	s_or_b32 s8, s18, 16
	s_lshl_b32 s0, s3, 11
	s_lshl_b64 s[10:11], s[6:7], 8
	s_ashr_i32 s19, s18, 31
	s_ashr_i32 s9, s8, 31
	s_mul_i32 s7, s6, 0x3000
	s_ashr_i32 s23, s0, 31
	s_mul_hi_i32 s5, s6, 0x3000
	s_add_u32 s22, s7, s0
	s_addc_u32 s23, s5, s23
	s_lshl_b64 s[22:23], s[22:23], 5
	s_add_u32 s20, s20, s22
	s_addc_u32 s21, s21, s23
	v_ashrrev_i32_e32 v131, 31, v130
	v_lshl_add_u64 v[4:5], v[130:131], 4, s[20:21]
	v_add_u32_e32 v86, 0x200, v130
	global_load_dwordx4 v[70:73], v[4:5], off
	v_ashrrev_i32_e32 v87, 31, v86
	v_lshl_add_u64 v[4:5], v[86:87], 4, s[20:21]
	v_add_u32_e32 v106, 0x400, v130
	global_load_dwordx4 v[74:77], v[4:5], off
	v_ashrrev_i32_e32 v107, 31, v106
	v_lshl_add_u64 v[4:5], v[106:107], 4, s[20:21]
	v_add_u32_e32 v108, 0x600, v130
	global_load_dwordx4 v[78:81], v[4:5], off
	v_ashrrev_i32_e32 v109, 31, v108
	v_lshl_add_u64 v[4:5], v[108:109], 4, s[20:21]
	v_add_u32_e32 v110, 0x800, v130
	global_load_dwordx4 v[82:85], v[4:5], off
	v_ashrrev_i32_e32 v111, 31, v110
	v_lshl_add_u64 v[4:5], v[110:111], 4, s[20:21]
	v_add_u32_e32 v112, 0xa00, v130
	global_load_dwordx4 v[90:93], v[4:5], off
	v_ashrrev_i32_e32 v113, 31, v112
	v_lshl_add_u64 v[4:5], v[112:113], 4, s[20:21]
	v_add_u32_e32 v114, 0xc00, v130
	global_load_dwordx4 v[94:97], v[4:5], off
	v_ashrrev_i32_e32 v115, 31, v114
	v_lshl_add_u64 v[4:5], v[114:115], 4, s[20:21]
	v_add_u32_e32 v116, 0xe00, v130
	global_load_dwordx4 v[98:101], v[4:5], off
	v_ashrrev_i32_e32 v117, 31, v116
	v_lshl_add_u64 v[4:5], v[116:117], 4, s[20:21]
	global_load_dwordx4 v[102:105], v[4:5], off
	v_mov_b32_e32 v67, 0
	v_or_b32_e32 v2, s10, v135
	v_mov_b32_e32 v3, s11
	v_and_b32_e32 v132, 48, v130
	v_mov_b32_e32 v133, v67
	v_lshl_add_u64 v[4:5], s[54:55], 0, v[132:133]
	s_mov_b64 s[10:11], 0xe400000
	v_lshl_add_u64 v[68:69], v[2:3], 0, s[18:19]
	v_lshl_add_u64 v[138:139], v[2:3], 0, s[8:9]
	v_lshl_add_u64 v[4:5], v[4:5], 0, s[10:11]
	v_lshlrev_b64 v[6:7], 9, v[68:69]
	v_lshlrev_b64 v[2:3], 9, v[138:139]
	v_lshl_add_u64 v[6:7], v[4:5], 0, v[6:7]
	v_lshl_add_u64 v[2:3], v[4:5], 0, v[2:3]
	global_load_dwordx4 v[58:61], v[6:7], off
	global_load_dwordx4 v[62:65], v[6:7], off offset:64
	global_load_dwordx4 v[50:53], v[6:7], off offset:128
	global_load_dwordx4 v[54:57], v[6:7], off offset:192
	global_load_dwordx4 v[42:45], v[6:7], off offset:256
	global_load_dwordx4 v[46:49], v[6:7], off offset:320
	global_load_dwordx4 v[34:37], v[6:7], off offset:384
	global_load_dwordx4 v[38:41], v[6:7], off offset:448
	global_load_dwordx4 v[10:13], v[2:3], off
	global_load_dwordx4 v[14:17], v[2:3], off offset:64
	global_load_dwordx4 v[18:21], v[2:3], off offset:128
	global_load_dwordx4 v[22:25], v[2:3], off offset:192
	global_load_dwordx4 v[26:29], v[2:3], off offset:256
	global_load_dwordx4 v[30:33], v[2:3], off offset:320
	global_load_dwordx4 v[6:9], v[2:3], off offset:384
	s_nop 0
	global_load_dwordx4 v[2:5], v[2:3], off offset:448
	v_and_b32_e32 v66, 0x1e0, v89
	v_and_b32_e32 v87, 16, v89
	v_add3_u32 v66, 0, v66, v87
	v_ashrrev_i32_e32 v87, 5, v130
	s_movk_i32 s5, 0x210
	v_mad_u64_u32 v[118:119], s[8:9], v87, s5, v[66:67]
	v_mul_u32_u24_e32 v133, 0x210, v135
	v_lshlrev_b32_e32 v134, 3, v88
	v_and_b32_e32 v140, 63, v130
	v_mov_b32_e32 v144, 0
	v_mov_b32_e32 v143, 0
	v_mov_b32_e32 v136, 0
	v_mov_b32_e32 v137, 0
	s_waitcnt vmcnt(23)
	ds_write_b128 v118, v[70:73]
	v_ashrrev_i32_e32 v70, 5, v86
	v_mad_u64_u32 v[70:71], s[8:9], v70, s5, v[66:67]
	s_waitcnt vmcnt(22)
	ds_write_b128 v70, v[74:77]
	v_ashrrev_i32_e32 v70, 5, v106
	v_mad_u64_u32 v[70:71], s[8:9], v70, s5, v[66:67]
	s_waitcnt vmcnt(21)
	ds_write_b128 v70, v[78:81]
	v_ashrrev_i32_e32 v70, 5, v108
	v_mad_u64_u32 v[70:71], s[8:9], v70, s5, v[66:67]
	s_waitcnt vmcnt(20)
	ds_write_b128 v70, v[82:85]
	v_ashrrev_i32_e32 v70, 5, v110
	v_mad_u64_u32 v[70:71], s[8:9], v70, s5, v[66:67]
	s_waitcnt vmcnt(19)
	ds_write_b128 v70, v[90:93]
	v_ashrrev_i32_e32 v70, 5, v112
	v_mad_u64_u32 v[70:71], s[8:9], v70, s5, v[66:67]
	s_waitcnt vmcnt(18)
	ds_write_b128 v70, v[94:97]
	v_ashrrev_i32_e32 v70, 5, v114
	v_mad_u64_u32 v[70:71], s[8:9], v70, s5, v[66:67]
	s_waitcnt vmcnt(17)
	ds_write_b128 v70, v[98:101]
	v_ashrrev_i32_e32 v70, 5, v116
	v_mad_u64_u32 v[70:71], s[8:9], v70, s5, v[66:67]
	v_and_b32_e32 v66, 32, v130
	s_waitcnt vmcnt(16)
	ds_write_b128 v70, v[102:105]
	v_add_u32_e32 v66, 0, v66
	v_and_b32_e32 v70, 16, v130
	v_add3_u32 v131, v66, v70, v133
	s_waitcnt lgkmcnt(0)
	s_barrier
	ds_read_b128 v[70:73], v131
	ds_read_b128 v[74:77], v131 offset:64
	s_waitcnt vmcnt(15) lgkmcnt(1)
	v_mfma_f32_16x16x32_bf16 v[78:81], v[58:61], v[70:73], 0
	ds_read_b128 v[82:85], v131 offset:128
	ds_read_b128 v[90:93], v131 offset:192
	ds_read_b128 v[94:97], v131 offset:256
	ds_read_b128 v[98:101], v131 offset:320
	ds_read_b128 v[102:105], v131 offset:384
	ds_read_b128 v[106:109], v131 offset:448
	s_waitcnt vmcnt(7)
	v_mfma_f32_16x16x32_bf16 v[70:73], v[10:13], v[70:73], 0
	s_and_b32 s5, s4, 0xffffffc0
	s_add_i32 s5, s5, 0
	s_add_i32 s5, s5, 0x10800
	s_waitcnt lgkmcnt(6)
	v_mfma_f32_16x16x32_bf16 v[78:81], v[62:65], v[74:77], v[78:81]
	v_add3_u32 v66, s5, v134, v133
	s_cmp_lt_i32 s3, 2
	s_cselect_b64 s[8:9], -1, 0
	s_waitcnt vmcnt(6)
	v_mfma_f32_16x16x32_bf16 v[70:73], v[14:17], v[74:77], v[70:73]
	s_and_b64 s[10:11], s[8:9], exec
	s_cselect_b32 s5, 16, 2
	s_cmp_lt_i32 s1, s5
	s_waitcnt lgkmcnt(5)
	v_mfma_f32_16x16x32_bf16 v[78:81], v[50:53], v[82:85], v[78:81]
	s_cselect_b64 s[18:19], -1, 0
	s_cmp_ge_i32 s1, s5
	s_waitcnt vmcnt(5)
	v_mfma_f32_16x16x32_bf16 v[70:73], v[18:21], v[82:85], v[70:73]
	s_waitcnt lgkmcnt(4)
	v_mfma_f32_16x16x32_bf16 v[78:81], v[54:57], v[90:93], v[78:81]
	s_waitcnt vmcnt(4)
	v_mfma_f32_16x16x32_bf16 v[70:73], v[22:25], v[90:93], v[70:73]
	s_waitcnt lgkmcnt(3)
	v_mfma_f32_16x16x32_bf16 v[78:81], v[42:45], v[94:97], v[78:81]
	s_waitcnt vmcnt(3)
	v_mfma_f32_16x16x32_bf16 v[70:73], v[26:29], v[94:97], v[70:73]
	s_waitcnt lgkmcnt(2)
	v_mfma_f32_16x16x32_bf16 v[78:81], v[46:49], v[98:101], v[78:81]
	s_waitcnt vmcnt(2)
	v_mfma_f32_16x16x32_bf16 v[70:73], v[30:33], v[98:101], v[70:73]
	s_waitcnt lgkmcnt(1)
	v_mfma_f32_16x16x32_bf16 v[78:81], v[34:37], v[102:105], v[78:81]
	s_waitcnt vmcnt(1)
	v_mfma_f32_16x16x32_bf16 v[70:73], v[6:9], v[102:105], v[70:73]
	s_waitcnt lgkmcnt(0)
	v_mfma_f32_16x16x32_bf16 v[78:81], v[38:41], v[106:109], v[78:81]
	s_waitcnt vmcnt(0)
	v_mfma_f32_16x16x32_bf16 v[70:73], v[2:5], v[106:109], v[70:73]
	s_nop 5
	v_cvt_pk_bf16_f32 v74, v78, v79
	v_cvt_pk_bf16_f32 v75, v80, v81
	v_cvt_pk_bf16_f32 v70, v70, v71
	v_cvt_pk_bf16_f32 v71, v72, v73
	ds_write2_b64 v66, v[74:75], v[70:71] offset1:4
	ds_read_b128 v[70:73], v131 offset:8448
	ds_read_b128 v[74:77], v131 offset:8512
	s_waitcnt lgkmcnt(1)
	v_mfma_f32_16x16x32_bf16 v[78:81], v[58:61], v[70:73], 0
	ds_read_b128 v[82:85], v131 offset:8576
	ds_read_b128 v[86:89], v131 offset:8640
	ds_read_b128 v[90:93], v131 offset:8704
	ds_read_b128 v[94:97], v131 offset:8768
	ds_read_b128 v[98:101], v131 offset:8832
	ds_read_b128 v[102:105], v131 offset:8896
	v_mfma_f32_16x16x32_bf16 v[70:73], v[10:13], v[70:73], 0
	s_waitcnt lgkmcnt(6)
	v_mfma_f32_16x16x32_bf16 v[78:81], v[62:65], v[74:77], v[78:81]
	v_mfma_f32_16x16x32_bf16 v[70:73], v[14:17], v[74:77], v[70:73]
	s_waitcnt lgkmcnt(5)
	v_mfma_f32_16x16x32_bf16 v[78:81], v[50:53], v[82:85], v[78:81]
	v_mfma_f32_16x16x32_bf16 v[70:73], v[18:21], v[82:85], v[70:73]
	s_waitcnt lgkmcnt(4)
	v_mfma_f32_16x16x32_bf16 v[78:81], v[54:57], v[86:89], v[78:81]
	v_mfma_f32_16x16x32_bf16 v[70:73], v[22:25], v[86:89], v[70:73]
	s_waitcnt lgkmcnt(3)
	v_mfma_f32_16x16x32_bf16 v[78:81], v[42:45], v[90:93], v[78:81]
	v_mfma_f32_16x16x32_bf16 v[70:73], v[26:29], v[90:93], v[70:73]
	s_waitcnt lgkmcnt(2)
	v_mfma_f32_16x16x32_bf16 v[78:81], v[46:49], v[94:97], v[78:81]
	v_mfma_f32_16x16x32_bf16 v[70:73], v[30:33], v[94:97], v[70:73]
	s_waitcnt lgkmcnt(1)
	v_mfma_f32_16x16x32_bf16 v[78:81], v[34:37], v[98:101], v[78:81]
	v_mfma_f32_16x16x32_bf16 v[70:73], v[6:9], v[98:101], v[70:73]
	s_waitcnt lgkmcnt(0)
	v_mfma_f32_16x16x32_bf16 v[78:81], v[38:41], v[102:105], v[78:81]
	v_mfma_f32_16x16x32_bf16 v[70:73], v[2:5], v[102:105], v[70:73]
	s_nop 6
	v_cvt_pk_bf16_f32 v74, v78, v79
	v_cvt_pk_bf16_f32 v75, v80, v81
	v_cvt_pk_bf16_f32 v70, v70, v71
	v_cvt_pk_bf16_f32 v71, v72, v73
	v_add_u32_e32 v72, 0x2000, v66
	ds_write2_b64 v72, v[74:75], v[70:71] offset0:32 offset1:36
	ds_read_b128 v[70:73], v131 offset:16896
	ds_read_b128 v[74:77], v131 offset:16960
	s_waitcnt lgkmcnt(1)
	v_mfma_f32_16x16x32_bf16 v[78:81], v[58:61], v[70:73], 0
	ds_read_b128 v[82:85], v131 offset:17024
	ds_read_b128 v[86:89], v131 offset:17088
	ds_read_b128 v[90:93], v131 offset:17152
	ds_read_b128 v[94:97], v131 offset:17216
	ds_read_b128 v[98:101], v131 offset:17280
	ds_read_b128 v[102:105], v131 offset:17344
	v_mfma_f32_16x16x32_bf16 v[70:73], v[10:13], v[70:73], 0
	s_waitcnt lgkmcnt(6)
	v_mfma_f32_16x16x32_bf16 v[78:81], v[62:65], v[74:77], v[78:81]
	v_mfma_f32_16x16x32_bf16 v[70:73], v[14:17], v[74:77], v[70:73]
	s_waitcnt lgkmcnt(5)
	v_mfma_f32_16x16x32_bf16 v[78:81], v[50:53], v[82:85], v[78:81]
	v_mfma_f32_16x16x32_bf16 v[70:73], v[18:21], v[82:85], v[70:73]
	s_waitcnt lgkmcnt(4)
	v_mfma_f32_16x16x32_bf16 v[78:81], v[54:57], v[86:89], v[78:81]
	v_mfma_f32_16x16x32_bf16 v[70:73], v[22:25], v[86:89], v[70:73]
	s_waitcnt lgkmcnt(3)
	v_mfma_f32_16x16x32_bf16 v[78:81], v[42:45], v[90:93], v[78:81]
	v_mfma_f32_16x16x32_bf16 v[70:73], v[26:29], v[90:93], v[70:73]
	s_waitcnt lgkmcnt(2)
	v_mfma_f32_16x16x32_bf16 v[78:81], v[46:49], v[94:97], v[78:81]
	v_mfma_f32_16x16x32_bf16 v[70:73], v[30:33], v[94:97], v[70:73]
	s_waitcnt lgkmcnt(1)
	v_mfma_f32_16x16x32_bf16 v[78:81], v[34:37], v[98:101], v[78:81]
	v_mfma_f32_16x16x32_bf16 v[70:73], v[6:9], v[98:101], v[70:73]
	s_waitcnt lgkmcnt(0)
	v_mfma_f32_16x16x32_bf16 v[78:81], v[38:41], v[102:105], v[78:81]
	v_mfma_f32_16x16x32_bf16 v[70:73], v[2:5], v[102:105], v[70:73]
	s_nop 6
	v_cvt_pk_bf16_f32 v74, v78, v79
	v_cvt_pk_bf16_f32 v75, v80, v81
	v_cvt_pk_bf16_f32 v70, v70, v71
	v_cvt_pk_bf16_f32 v71, v72, v73
	v_add_u32_e32 v72, 0x4000, v66
	ds_write2_b64 v72, v[74:75], v[70:71] offset0:64 offset1:68
	ds_read_b128 v[70:73], v131 offset:25344
	ds_read_b128 v[74:77], v131 offset:25408
	s_waitcnt lgkmcnt(1)
	v_mfma_f32_16x16x32_bf16 v[78:81], v[58:61], v[70:73], 0
	ds_read_b128 v[82:85], v131 offset:25472
	ds_read_b128 v[86:89], v131 offset:25536
	ds_read_b128 v[90:93], v131 offset:25600
	ds_read_b128 v[94:97], v131 offset:25664
	ds_read_b128 v[98:101], v131 offset:25728
	ds_read_b128 v[102:105], v131 offset:25792
	v_mfma_f32_16x16x32_bf16 v[70:73], v[10:13], v[70:73], 0
	s_waitcnt lgkmcnt(6)
	v_mfma_f32_16x16x32_bf16 v[78:81], v[62:65], v[74:77], v[78:81]
	v_mfma_f32_16x16x32_bf16 v[70:73], v[14:17], v[74:77], v[70:73]
	s_waitcnt lgkmcnt(5)
	v_mfma_f32_16x16x32_bf16 v[78:81], v[50:53], v[82:85], v[78:81]
	v_mfma_f32_16x16x32_bf16 v[70:73], v[18:21], v[82:85], v[70:73]
	s_waitcnt lgkmcnt(4)
	v_mfma_f32_16x16x32_bf16 v[78:81], v[54:57], v[86:89], v[78:81]
	v_mfma_f32_16x16x32_bf16 v[70:73], v[22:25], v[86:89], v[70:73]
	s_waitcnt lgkmcnt(3)
	v_mfma_f32_16x16x32_bf16 v[78:81], v[42:45], v[90:93], v[78:81]
	v_mfma_f32_16x16x32_bf16 v[70:73], v[26:29], v[90:93], v[70:73]
	s_waitcnt lgkmcnt(2)
	v_mfma_f32_16x16x32_bf16 v[78:81], v[46:49], v[94:97], v[78:81]
	v_mfma_f32_16x16x32_bf16 v[70:73], v[30:33], v[94:97], v[70:73]
	s_waitcnt lgkmcnt(1)
	v_mfma_f32_16x16x32_bf16 v[78:81], v[34:37], v[98:101], v[78:81]
	v_mfma_f32_16x16x32_bf16 v[70:73], v[6:9], v[98:101], v[70:73]
	s_waitcnt lgkmcnt(0)
	v_mfma_f32_16x16x32_bf16 v[74:77], v[38:41], v[102:105], v[78:81]
	v_mfma_f32_16x16x32_bf16 v[70:73], v[2:5], v[102:105], v[70:73]
	s_nop 6
	v_cvt_pk_bf16_f32 v74, v74, v75
	v_cvt_pk_bf16_f32 v75, v76, v77
	v_cvt_pk_bf16_f32 v70, v70, v71
	v_cvt_pk_bf16_f32 v71, v72, v73
	v_add_u32_e32 v72, 0x6000, v66
	ds_write2_b64 v72, v[74:75], v[70:71] offset0:96 offset1:100
	ds_read_b128 v[70:73], v131 offset:33792
	ds_read_b128 v[74:77], v131 offset:33856
	s_waitcnt lgkmcnt(1)
	v_mfma_f32_16x16x32_bf16 v[78:81], v[58:61], v[70:73], 0
	ds_read_b128 v[82:85], v131 offset:33920
	ds_read_b128 v[86:89], v131 offset:33984
	ds_read_b128 v[90:93], v131 offset:34048
	ds_read_b128 v[94:97], v131 offset:34112
	ds_read_b128 v[98:101], v131 offset:34176
	ds_read_b128 v[102:105], v131 offset:34240
	v_mfma_f32_16x16x32_bf16 v[70:73], v[10:13], v[70:73], 0
	s_waitcnt lgkmcnt(6)
	v_mfma_f32_16x16x32_bf16 v[78:81], v[62:65], v[74:77], v[78:81]
	v_mfma_f32_16x16x32_bf16 v[70:73], v[14:17], v[74:77], v[70:73]
	s_waitcnt lgkmcnt(5)
	v_mfma_f32_16x16x32_bf16 v[78:81], v[50:53], v[82:85], v[78:81]
	v_mfma_f32_16x16x32_bf16 v[70:73], v[18:21], v[82:85], v[70:73]
	s_waitcnt lgkmcnt(4)
	v_mfma_f32_16x16x32_bf16 v[78:81], v[54:57], v[86:89], v[78:81]
	v_mfma_f32_16x16x32_bf16 v[70:73], v[22:25], v[86:89], v[70:73]
	s_waitcnt lgkmcnt(3)
	v_mfma_f32_16x16x32_bf16 v[78:81], v[42:45], v[90:93], v[78:81]
	v_mfma_f32_16x16x32_bf16 v[70:73], v[26:29], v[90:93], v[70:73]
	s_waitcnt lgkmcnt(2)
	v_mfma_f32_16x16x32_bf16 v[78:81], v[46:49], v[94:97], v[78:81]
	v_mfma_f32_16x16x32_bf16 v[70:73], v[30:33], v[94:97], v[70:73]
	s_waitcnt lgkmcnt(1)
	v_mfma_f32_16x16x32_bf16 v[78:81], v[34:37], v[98:101], v[78:81]
	v_mfma_f32_16x16x32_bf16 v[70:73], v[6:9], v[98:101], v[70:73]
	s_waitcnt lgkmcnt(0)
	v_mfma_f32_16x16x32_bf16 v[78:81], v[38:41], v[102:105], v[78:81]
	v_mfma_f32_16x16x32_bf16 v[70:73], v[2:5], v[102:105], v[70:73]
	s_nop 6
	v_cvt_pk_bf16_f32 v74, v78, v79
	v_cvt_pk_bf16_f32 v75, v80, v81
	v_cvt_pk_bf16_f32 v70, v70, v71
	v_cvt_pk_bf16_f32 v71, v72, v73
	v_add_u32_e32 v72, 0x8000, v66
	ds_write2_b64 v72, v[74:75], v[70:71] offset0:128 offset1:132
	ds_read_b128 v[70:73], v131 offset:42240
	ds_read_b128 v[74:77], v131 offset:42304
	s_waitcnt lgkmcnt(1)
	v_mfma_f32_16x16x32_bf16 v[78:81], v[58:61], v[70:73], 0
	ds_read_b128 v[82:85], v131 offset:42368
	ds_read_b128 v[86:89], v131 offset:42432
	ds_read_b128 v[90:93], v131 offset:42496
	ds_read_b128 v[94:97], v131 offset:42560
	ds_read_b128 v[98:101], v131 offset:42624
	ds_read_b128 v[102:105], v131 offset:42688
	v_mfma_f32_16x16x32_bf16 v[70:73], v[10:13], v[70:73], 0
	s_waitcnt lgkmcnt(6)
	v_mfma_f32_16x16x32_bf16 v[78:81], v[62:65], v[74:77], v[78:81]
	v_mfma_f32_16x16x32_bf16 v[70:73], v[14:17], v[74:77], v[70:73]
	s_waitcnt lgkmcnt(5)
	v_mfma_f32_16x16x32_bf16 v[78:81], v[50:53], v[82:85], v[78:81]
	v_mfma_f32_16x16x32_bf16 v[70:73], v[18:21], v[82:85], v[70:73]
	s_waitcnt lgkmcnt(4)
	v_mfma_f32_16x16x32_bf16 v[78:81], v[54:57], v[86:89], v[78:81]
	v_mfma_f32_16x16x32_bf16 v[70:73], v[22:25], v[86:89], v[70:73]
	s_waitcnt lgkmcnt(3)
	v_mfma_f32_16x16x32_bf16 v[78:81], v[42:45], v[90:93], v[78:81]
	v_mfma_f32_16x16x32_bf16 v[70:73], v[26:29], v[90:93], v[70:73]
	s_waitcnt lgkmcnt(2)
	v_mfma_f32_16x16x32_bf16 v[78:81], v[46:49], v[94:97], v[78:81]
	v_mfma_f32_16x16x32_bf16 v[70:73], v[30:33], v[94:97], v[70:73]
	s_waitcnt lgkmcnt(1)
	v_mfma_f32_16x16x32_bf16 v[78:81], v[34:37], v[98:101], v[78:81]
	v_mfma_f32_16x16x32_bf16 v[70:73], v[6:9], v[98:101], v[70:73]
	s_waitcnt lgkmcnt(0)
	v_mfma_f32_16x16x32_bf16 v[78:81], v[38:41], v[102:105], v[78:81]
	v_mfma_f32_16x16x32_bf16 v[70:73], v[2:5], v[102:105], v[70:73]
	s_nop 6
	v_cvt_pk_bf16_f32 v74, v78, v79
	v_cvt_pk_bf16_f32 v75, v80, v81
	v_cvt_pk_bf16_f32 v70, v70, v71
	v_cvt_pk_bf16_f32 v71, v72, v73
	v_add_u32_e32 v72, 0xa000, v66
	ds_write2_b64 v72, v[74:75], v[70:71] offset0:160 offset1:164
	ds_read_b128 v[70:73], v131 offset:50688
	ds_read_b128 v[74:77], v131 offset:50752
	s_waitcnt lgkmcnt(1)
	v_mfma_f32_16x16x32_bf16 v[78:81], v[58:61], v[70:73], 0
	ds_read_b128 v[82:85], v131 offset:50816
	ds_read_b128 v[86:89], v131 offset:50880
	ds_read_b128 v[90:93], v131 offset:50944
	ds_read_b128 v[94:97], v131 offset:51008
	ds_read_b128 v[98:101], v131 offset:51072
	ds_read_b128 v[102:105], v131 offset:51136
	v_mfma_f32_16x16x32_bf16 v[70:73], v[10:13], v[70:73], 0
	s_waitcnt lgkmcnt(6)
	v_mfma_f32_16x16x32_bf16 v[78:81], v[62:65], v[74:77], v[78:81]
	v_mfma_f32_16x16x32_bf16 v[70:73], v[14:17], v[74:77], v[70:73]
	s_waitcnt lgkmcnt(5)
	v_mfma_f32_16x16x32_bf16 v[78:81], v[50:53], v[82:85], v[78:81]
	v_mfma_f32_16x16x32_bf16 v[70:73], v[18:21], v[82:85], v[70:73]
	s_waitcnt lgkmcnt(4)
	v_mfma_f32_16x16x32_bf16 v[78:81], v[54:57], v[86:89], v[78:81]
	v_mfma_f32_16x16x32_bf16 v[70:73], v[22:25], v[86:89], v[70:73]
	s_waitcnt lgkmcnt(3)
	v_mfma_f32_16x16x32_bf16 v[78:81], v[42:45], v[90:93], v[78:81]
	v_mfma_f32_16x16x32_bf16 v[70:73], v[26:29], v[90:93], v[70:73]
	s_waitcnt lgkmcnt(2)
	v_mfma_f32_16x16x32_bf16 v[78:81], v[46:49], v[94:97], v[78:81]
	v_mfma_f32_16x16x32_bf16 v[70:73], v[30:33], v[94:97], v[70:73]
	s_waitcnt lgkmcnt(1)
	v_mfma_f32_16x16x32_bf16 v[78:81], v[34:37], v[98:101], v[78:81]
	v_mfma_f32_16x16x32_bf16 v[70:73], v[6:9], v[98:101], v[70:73]
	s_waitcnt lgkmcnt(0)
	v_mfma_f32_16x16x32_bf16 v[78:81], v[38:41], v[102:105], v[78:81]
	v_mfma_f32_16x16x32_bf16 v[70:73], v[2:5], v[102:105], v[70:73]
	s_nop 6
	v_cvt_pk_bf16_f32 v74, v78, v79
	v_cvt_pk_bf16_f32 v75, v80, v81
	v_cvt_pk_bf16_f32 v70, v70, v71
	v_cvt_pk_bf16_f32 v71, v72, v73
	v_add_u32_e32 v72, 0xc000, v66
	ds_write2_b64 v72, v[74:75], v[70:71] offset0:192 offset1:196
	ds_read_b128 v[70:73], v131 offset:59136
	ds_read_b128 v[74:77], v131 offset:59200
	s_waitcnt lgkmcnt(1)
	v_mfma_f32_16x16x32_bf16 v[58:61], v[58:61], v[70:73], 0
	v_mfma_f32_16x16x32_bf16 v[10:13], v[10:13], v[70:73], 0
	s_waitcnt lgkmcnt(0)
	v_mfma_f32_16x16x32_bf16 v[58:61], v[62:65], v[74:77], v[58:61]
	ds_read_b128 v[62:65], v131 offset:59264
	ds_read_b128 v[78:81], v131 offset:59328
	v_mfma_f32_16x16x32_bf16 v[10:13], v[14:17], v[74:77], v[10:13]
	s_waitcnt lgkmcnt(1)
	v_mfma_f32_16x16x32_bf16 v[50:53], v[50:53], v[62:65], v[58:61]
	v_mfma_f32_16x16x32_bf16 v[10:13], v[18:21], v[62:65], v[10:13]
	s_waitcnt lgkmcnt(0)
	v_mfma_f32_16x16x32_bf16 v[50:53], v[54:57], v[78:81], v[50:53]
	ds_read_b128 v[54:57], v131 offset:59392
	ds_read_b128 v[58:61], v131 offset:59456
	v_mfma_f32_16x16x32_bf16 v[10:13], v[22:25], v[78:81], v[10:13]
	s_waitcnt lgkmcnt(1)
	v_mfma_f32_16x16x32_bf16 v[42:45], v[42:45], v[54:57], v[50:53]
	v_mfma_f32_16x16x32_bf16 v[10:13], v[26:29], v[54:57], v[10:13]
	s_waitcnt lgkmcnt(0)
	v_mfma_f32_16x16x32_bf16 v[42:45], v[46:49], v[58:61], v[42:45]
	ds_read_b128 v[46:49], v131 offset:59520
	ds_read_b128 v[50:53], v131 offset:59584
	v_mfma_f32_16x16x32_bf16 v[10:13], v[30:33], v[58:61], v[10:13]
	s_waitcnt lgkmcnt(1)
	v_mfma_f32_16x16x32_bf16 v[34:37], v[34:37], v[46:49], v[42:45]
	v_mfma_f32_16x16x32_bf16 v[6:9], v[6:9], v[46:49], v[10:13]
	s_waitcnt lgkmcnt(0)
	v_mfma_f32_16x16x32_bf16 v[34:37], v[38:41], v[50:53], v[34:37]
	v_mfma_f32_16x16x32_bf16 v[2:5], v[2:5], v[50:53], v[6:9]
	s_nop 6
	v_cvt_pk_bf16_f32 v10, v34, v35
	v_cvt_pk_bf16_f32 v11, v36, v37
	v_cvt_pk_bf16_f32 v2, v2, v3
	v_cvt_pk_bf16_f32 v3, v4, v5
	v_add_u32_e32 v4, 0xe000, v66
	ds_write2_b64 v4, v[10:11], v[2:3] offset0:224 offset1:228
	s_cbranch_scc1 .LBB0_283
	s_bfe_u32 s7, s4, 0x10006
	s_lshl_b32 s10, s7, 11
	s_lshl_b32 s7, s6, 6
	s_add_i32 s11, s10, s7
	v_or_b32_e32 v2, s11, v140
	v_readlane_b32 s12, v242, 36
	v_ashrrev_i32_e32 v3, 31, v2
	v_readlane_b32 s13, v242, 37
	s_andn2_b64 vcc, exec, s[16:17]
	v_mov_b32_e32 v143, 0
	v_lshl_add_u64 v[2:3], v[2:3], 3, s[12:13]
	global_load_dwordx2 v[136:137], v[2:3], off
	v_mov_b32_e32 v144, 0
	s_cbranch_vccnz .LBB0_283
	s_lshl_b32 s11, s3, 12
	s_or_b32 s10, s11, s10
	s_add_i32 s7, s10, s7
	s_addk_i32 s7, 0xe000
	v_or_b32_e32 v2, s7, v140
	v_ashrrev_i32_e32 v3, 31, v2
	v_lshlrev_b64 v[2:3], 2, v[2:3]
	v_lshl_add_u64 v[4:5], s[62:63], 0, v[2:3]
	v_lshl_add_u64 v[2:3], s[64:65], 0, v[2:3]
	global_load_dword v143, v[4:5], off
	global_load_dword v144, v[2:3], off

.Lgb4_4_follow:
	s_branch .LBB0_442
	v_mov_b32_e32 v2, 4
	s_mov_b32 s99, 0

.LBB0_442:
	s_or_b64 exec, exec, s[6:7]
	v_readlane_b32 s0, v242, 38
	s_add_u32 s84, s54, 0x3400000
	v_mov_b32_e32 v215, v0
	v_readlane_b32 s1, v242, 39
	s_addc_u32 s85, s55, 0
	s_waitcnt lgkmcnt(0)
	s_and_b64 vcc, exec, s[0:1]
	v_readfirstlane_b32 s3, v215
	s_cbranch_vccz .Lh4b_main
	v_readfirstlane_b32 s98, v0
	s_cmp_gt_u32 s98, 63
	s_cbranch_scc1 .Lh4b_done
	s_getreg_b32 s98, hwreg(HW_REG_XCC_ID, 0, 4)
	s_lshl_b32 s98, s98, 8
	v_mov_b32_e32 v232, s98
	v_add_u32_e32 v232, 0x6400, v232
	s_mov_b32 s98, 0
.Lh4b_spin:
	global_load_dword v233, v232, s[54:55] sc1
	s_waitcnt vmcnt(0)
	v_readfirstlane_b32 s99, v233
	s_cmp_ge_u32 s99, 4
	s_cbranch_scc1 .Lh4b_done
	s_add_i32 s98, s98, 1
	s_cmp_gt_u32 s98, 0x40000
	s_cbranch_scc1 .Lh4b_done
	s_sleep 1
	s_branch .Lh4b_spin

.Lh4b_main:
	v_lshlrev_b32_e32 v1, 4, v215
	v_add_u32_e32 v2, 0x2000, v1
	v_ashrrev_i32_e32 v3, 31, v2
	v_lshrrev_b32_e32 v3, 22, v3
	v_add_u32_e32 v3, v2, v3
	v_ashrrev_i32_e32 v10, 10, v3
	v_mul_i32_i24_e32 v3, 0x400, v10
	v_sub_u32_e32 v2, v2, v3
	v_lshrrev_b32_e32 v3, 4, v2
	v_bitop3_b32 v2, v3, v2, 32 bitop3:0x6c
	v_ashrrev_i32_e32 v3, 31, v2
	v_lshrrev_b32_e32 v3, 26, v3
	v_add_u32_e32 v3, v2, v3
	v_lshlrev_b32_e32 v4, 3, v10
	v_ashrrev_i32_e32 v11, 6, v3
	v_and_b32_e32 v4, -16, v4
	v_add_u32_e32 v4, v11, v4
	v_and_b32_e32 v5, 3, v11
	s_mov_b32 s0, 0x1fffe0
	v_lshrrev_b32_e32 v6, 2, v4
	v_lshlrev_b32_e32 v7, 1, v4
	v_and_b32_e32 v3, 0xc0, v3
	v_and_or_b32 v5, v4, s0, v5
	v_and_b32_e32 v6, 4, v6
	v_and_b32_e32 v7, 24, v7
	v_sub_u32_e32 v2, v2, v3
	v_mov_b32_e32 v3, 1
	v_or3_b32 v5, v5, v6, v7
	v_lshlrev_b32_e32 v6, 5, v10
	v_ashrrev_i16_sdwa v2, v3, sext(v2) dst_sel:DWORD dst_unused:UNUSED_PAD src0_sel:DWORD src1_sel:BYTE_0
	v_and_b32_e32 v6, 32, v6
	v_bfe_i32 v12, v2, 0, 16
	v_add_lshl_u32 v2, v6, v12, 1
	v_lshl_add_u32 v130, v5, 11, v2
	v_lshl_add_u32 v132, v4, 11, v2
	v_bfe_i32 v2, v215, 27, 1
	v_lshrrev_b32_e32 v2, 22, v2
	v_add_u32_e32 v2, v1, v2
	v_and_b32_e32 v2, 0xfffffc00, v2
	v_sub_u32_e32 v1, v1, v2
	v_lshrrev_b32_e32 v2, 4, v1
	v_ashrrev_i32_e32 v4, 31, v215
	v_bitop3_b32 v1, v2, v1, 32 bitop3:0x6c
	v_lshrrev_b32_e32 v4, 26, v4
	v_ashrrev_i32_e32 v2, 31, v1
	v_add_u32_e32 v4, v215, v4
	v_lshrrev_b32_e32 v2, 26, v2
	v_ashrrev_i32_e32 v14, 6, v4
	v_add_u32_e32 v2, v1, v2
	v_lshlrev_b32_e32 v4, 3, v14
	v_ashrrev_i32_e32 v13, 6, v2
	v_and_b32_e32 v4, -16, v4
	v_add_u32_e32 v4, v13, v4
	v_and_b32_e32 v5, 3, v13
	s_ashr_i32 s62, s38, 31
	v_and_or_b32 v5, v4, s0, v5
	s_lshr_b32 s0, s62, 29
	s_add_i32 s0, s38, s0
	s_ashr_i32 s34, s3, 6
	s_ashr_i32 s1, s0, 3
	s_and_b32 s0, s0, -8
	s_ashr_i32 s4, s3, 8
	s_lshl_b32 s37, s34, 10
	s_sub_i32 s0, s38, s0
	s_cmp_lt_i32 s0, 0
	s_cselect_b32 s5, 25, 24
	s_mul_i32 s0, s0, s5
	s_add_i32 s0, s0, s1
	s_mul_hi_i32 s1, s0, 0x2aaaaaab
	s_lshr_b32 s5, s1, 31
	s_ashr_i32 s1, s1, 2
	s_add_i32 s1, s1, s5
	s_mul_i32 s5, s1, 6
	s_mul_i32 s1, s1, 24
	s_sub_i32 s0, s0, s1
	s_bfe_i32 s1, s0, 0x80000
	s_mul_i32 s1, s1, 43
	s_bfe_u32 s6, s1, 0x1000f
	s_bfe_u32 s1, s1, 0x80008
	s_add_i32 s6, s1, s6
	s_mul_i32 s1, s6, 6
	s_sub_i32 s0, s0, s1
	s_sext_i32_i8 s0, s0
	v_lshrrev_b32_e32 v6, 2, v4
	v_lshlrev_b32_e32 v7, 1, v4
	v_and_b32_e32 v2, 0xc0, v2
	s_add_i32 s86, s5, s0
	v_and_b32_e32 v6, 4, v6
	v_and_b32_e32 v7, 24, v7
	v_sub_u32_e32 v1, v1, v2
	s_ashr_i32 s87, s86, 31
	s_bfe_i64 s[8:9], s[6:7], 0x80000
	v_or3_b32 v5, v5, v6, v7
	v_lshlrev_b32_e32 v6, 5, v14
	v_ashrrev_i16_sdwa v1, v3, sext(v1) dst_sel:DWORD dst_unused:UNUSED_PAD src0_sel:DWORD src1_sel:BYTE_0
	s_lshl_b64 s[0:1], s[86:87], 19
	s_lshl_b64 s[8:9], s[8:9], 19
	v_and_b32_e32 v6, 32, v6
	v_bfe_i32 v15, v1, 0, 16
	s_add_u32 s26, s70, s8
	v_add_lshl_u32 v1, v6, v15, 1
	s_addc_u32 s27, s71, s9
	s_add_i32 s63, s37, 0
	v_lshl_add_u32 v134, v5, 11, v1
	s_add_i32 m0, s63, 0x10000
	v_lshl_add_u32 v136, v4, 11, v1
	v_readfirstlane_b32 s98, v0
	s_cmp_gt_u32 s98, 63
	s_cbranch_scc1 .Lh4a_done
	s_getreg_b32 s98, hwreg(HW_REG_XCC_ID, 0, 4)
	s_lshl_b32 s98, s98, 8
	v_mov_b32_e32 v232, s98
	v_add_u32_e32 v232, 0x6400, v232
	s_mov_b32 s98, 0

.Lh4a_done:
	s_barrier
	global_load_lds_dwordx4 v134, s[26:27]
	s_add_i32 m0, s63, 0x12000
	s_add_u32 s8, s26, 0x40000
	global_load_lds_dwordx4 v130, s[26:27]
	s_addc_u32 s9, s27, 0
	s_add_i32 m0, s63, 0x14000
	v_mov_b32_e32 v135, 0
	global_load_lds_dwordx4 v134, s[8:9]
	s_add_i32 m0, s63, 0x16000
	s_add_u32 s10, s60, s0
	s_addc_u32 s11, s61, s1
	s_add_i32 s0, s63, 0x2000
	global_load_lds_dwordx4 v130, s[8:9]
	s_mov_b32 m0, s63
	s_add_u32 s8, s10, 0x40000
	global_load_lds_dwordx4 v136, s[10:11]
	s_mov_b32 m0, s0
	s_addc_u32 s9, s11, 0
	s_add_i32 s1, s63, 0x4000
	global_load_lds_dwordx4 v132, s[10:11]
	s_mov_b32 m0, s1
	s_add_i32 s64, s63, 0x6000
	global_load_lds_dwordx4 v136, s[8:9]
	s_mov_b32 m0, s64
	v_mov_b32_e32 v131, v135
	global_load_lds_dwordx4 v132, s[8:9]
	v_mov_b32_e32 v137, v135
	v_mov_b32_e32 v133, v135
	s_mov_b32 s65, 0
	v_lshl_add_u64 v[8:9], s[26:27], 0, v[134:135]
	v_lshl_add_u64 v[6:7], s[26:27], 0, v[130:131]
	v_lshl_add_u64 v[4:5], s[10:11], 0, v[136:137]
	s_cmp_lg_u32 s4, 1
	v_lshl_add_u64 v[2:3], s[10:11], 0, v[132:133]
	s_cbranch_scc1 .LBB0_445
	s_barrier

.Lgb4_5_follow:
	s_branch .LBB0_572
	v_mov_b32_e32 v2, 5
	s_mov_b32 s99, 0

.LBB0_572:
	s_or_b64 exec, exec, s[6:7]
	v_mov_b32_e32 v12, v0
	s_waitcnt lgkmcnt(0)
	s_cmpk_gt_i32 s38, 0x2ff
	v_readfirstlane_b32 s4, v12
	s_cbranch_scc0 .Lh5b_main
	v_readfirstlane_b32 s98, v0
	s_cmp_gt_u32 s98, 63
	s_cbranch_scc1 .Lh5b_done
	s_getreg_b32 s98, hwreg(HW_REG_XCC_ID, 0, 4)
	s_lshl_b32 s98, s98, 8
	v_mov_b32_e32 v226, s98
	v_add_u32_e32 v226, 0x6400, v226
	s_mov_b32 s98, 0
.Lh5b_spin:
	global_load_dword v227, v226, s[54:55] sc1
	s_waitcnt vmcnt(0)
	v_readfirstlane_b32 s99, v227
	s_cmp_ge_u32 s99, 5
	s_cbranch_scc1 .Lh5b_done
	s_add_i32 s98, s98, 1
	s_cmp_gt_u32 s98, 0x40000
	s_cbranch_scc1 .Lh5b_done
	s_sleep 1
	s_branch .Lh5b_spin

.Lh5b_main:
	v_lshlrev_b32_e32 v1, 4, v12
	v_add_u32_e32 v2, 0x2000, v1
	v_ashrrev_i32_e32 v3, 31, v2
	v_lshrrev_b32_e32 v3, 22, v3
	v_add_u32_e32 v3, v2, v3
	v_ashrrev_i32_e32 v10, 10, v3
	v_mul_i32_i24_e32 v3, 0x400, v10
	v_sub_u32_e32 v2, v2, v3
	v_lshrrev_b32_e32 v3, 4, v2
	v_bitop3_b32 v2, v3, v2, 32 bitop3:0x6c
	v_ashrrev_i32_e32 v3, 31, v2
	v_lshrrev_b32_e32 v3, 26, v3
	v_add_u32_e32 v3, v2, v3
	v_lshlrev_b32_e32 v4, 3, v10
	v_ashrrev_i32_e32 v11, 6, v3
	v_and_b32_e32 v4, -16, v4
	v_add_u32_e32 v4, v11, v4
	v_and_b32_e32 v5, 3, v11
	s_mov_b32 s0, 0x1fffe0
	v_lshrrev_b32_e32 v6, 2, v4
	v_lshlrev_b32_e32 v7, 1, v4
	v_and_b32_e32 v3, 0xc0, v3
	v_and_or_b32 v5, v4, s0, v5
	v_and_b32_e32 v6, 4, v6
	v_and_b32_e32 v7, 24, v7
	v_sub_u32_e32 v2, v2, v3
	v_mov_b32_e32 v3, 1
	v_or3_b32 v5, v5, v6, v7
	v_lshlrev_b32_e32 v6, 5, v10
	v_ashrrev_i16_sdwa v2, v3, sext(v2) dst_sel:DWORD dst_unused:UNUSED_PAD src0_sel:DWORD src1_sel:BYTE_0
	v_and_b32_e32 v6, 32, v6
	v_bfe_i32 v13, v2, 0, 16
	v_add_lshl_u32 v2, v6, v13, 1
	v_lshl_add_u32 v146, v5, 11, v2
	v_lshl_add_u32 v148, v4, 11, v2
	v_bfe_i32 v2, v12, 27, 1
	v_lshrrev_b32_e32 v2, 22, v2
	v_add_u32_e32 v2, v1, v2
	v_and_b32_e32 v2, 0xfffffc00, v2
	v_sub_u32_e32 v1, v1, v2
	v_lshrrev_b32_e32 v2, 4, v1
	v_ashrrev_i32_e32 v4, 31, v12
	v_bitop3_b32 v1, v2, v1, 32 bitop3:0x6c
	v_lshrrev_b32_e32 v4, 26, v4
	v_ashrrev_i32_e32 v2, 31, v1
	v_add_u32_e32 v4, v12, v4
	v_lshrrev_b32_e32 v2, 26, v2
	v_ashrrev_i32_e32 v15, 6, v4
	v_add_u32_e32 v2, v1, v2
	v_lshlrev_b32_e32 v4, 3, v15
	v_ashrrev_i32_e32 v14, 6, v2
	v_and_b32_e32 v4, -16, v4
	v_add_u32_e32 v4, v14, v4
	v_and_b32_e32 v5, 3, v14
	v_and_or_b32 v5, v4, s0, v5
	s_ashr_i32 s0, s38, 31
	s_lshr_b32 s1, s0, 29
	s_add_i32 s1, s38, s1
	s_ashr_i32 s7, s4, 6
	s_ashr_i32 s6, s1, 3
	s_and_b32 s1, s1, -8
	s_ashr_i32 s5, s4, 8
	s_lshl_b32 s3, s7, 10
	s_sub_i32 s14, s38, s1
	s_cmp_lt_i32 s14, 0
	s_movk_i32 s1, 0x61
	s_cselect_b32 s15, s1, 0x60
	s_mul_i32 s14, s14, s15
	s_add_i32 s14, s14, s6
	s_mul_hi_i32 s6, s14, 0x2aaaaaab
	s_lshr_b32 s15, s6, 31
	s_ashr_i32 s6, s6, 4
	s_add_i32 s6, s6, s15
	s_mul_i32 s15, s6, 6
	s_mulk_i32 s6, 0x60
	s_sub_i32 s14, s14, s6
	s_bfe_i32 s6, s14, 0x80000
	s_mul_i32 s6, s6, 43
	s_bfe_u32 s16, s6, 0x1000f
	s_bfe_u32 s6, s6, 0x80008
	s_add_i32 s6, s6, s16
	s_mul_i32 s16, s6, 6
	s_sub_i32 s14, s14, s16
	s_sext_i32_i8 s14, s14
	v_lshrrev_b32_e32 v6, 2, v4
	v_lshlrev_b32_e32 v7, 1, v4
	v_and_b32_e32 v2, 0xc0, v2
	s_add_i32 s40, s15, s14
	v_and_b32_e32 v6, 4, v6
	v_and_b32_e32 v7, 24, v7
	v_sub_u32_e32 v1, v1, v2
	s_ashr_i32 s41, s40, 31
	s_bfe_i64 s[16:17], s[6:7], 0x80000
	v_or3_b32 v5, v5, v6, v7
	v_lshlrev_b32_e32 v6, 5, v15
	v_ashrrev_i16_sdwa v1, v3, sext(v1) dst_sel:DWORD dst_unused:UNUSED_PAD src0_sel:DWORD src1_sel:BYTE_0
	s_lshl_b64 s[14:15], s[40:41], 19
	s_lshl_b64 s[16:17], s[16:17], 19
	v_and_b32_e32 v6, 32, v6
	v_bfe_i32 v16, v1, 0, 16
	s_add_u32 s56, s88, s16
	v_add_lshl_u32 v1, v6, v16, 1
	s_addc_u32 s57, s89, s17
	s_add_i32 s41, s3, 0
	v_lshl_add_u32 v150, v5, 11, v1
	s_add_i32 m0, s41, 0x10000
	v_lshl_add_u32 v152, v4, 11, v1
	v_readfirstlane_b32 s98, v0
	s_cmp_gt_u32 s98, 63
	s_cbranch_scc1 .Lh5a_done
	s_getreg_b32 s98, hwreg(HW_REG_XCC_ID, 0, 4)
	s_lshl_b32 s98, s98, 8
	v_mov_b32_e32 v226, s98
	v_add_u32_e32 v226, 0x6400, v226
	s_mov_b32 s98, 0

.Lh5a_done:
	s_barrier
	global_load_lds_dwordx4 v150, s[56:57]
	s_add_i32 m0, s41, 0x12000
	s_add_u32 s16, s56, 0x40000
	global_load_lds_dwordx4 v146, s[56:57]
	s_addc_u32 s17, s57, 0
	s_add_i32 m0, s41, 0x14000
	v_mov_b32_e32 v151, 0
	global_load_lds_dwordx4 v150, s[16:17]
	s_add_i32 m0, s41, 0x16000
	s_add_u32 s44, s66, s14
	s_addc_u32 s45, s67, s15
	s_add_i32 s60, s41, 0x2000
	global_load_lds_dwordx4 v146, s[16:17]
	s_mov_b32 m0, s41
	s_add_u32 s14, s44, 0x40000
	global_load_lds_dwordx4 v152, s[44:45]
	s_mov_b32 m0, s60
	s_addc_u32 s15, s45, 0
	s_add_i32 s61, s41, 0x4000
	global_load_lds_dwordx4 v148, s[44:45]
	s_mov_b32 m0, s61
	s_add_i32 s62, s41, 0x6000
	global_load_lds_dwordx4 v152, s[14:15]
	s_mov_b32 m0, s62
	v_mov_b32_e32 v147, v151
	global_load_lds_dwordx4 v148, s[14:15]
	v_mov_b32_e32 v153, v151
	v_mov_b32_e32 v149, v151
	s_cmp_eq_u32 s5, 1
	s_mov_b32 s63, 0
	v_lshl_add_u64 v[8:9], s[56:57], 0, v[150:151]
	v_lshl_add_u64 v[6:7], s[56:57], 0, v[146:147]
	v_lshl_add_u64 v[2:3], s[44:45], 0, v[152:153]
	s_cselect_b64 s[14:15], -1, 0
	s_cmp_lg_u32 s5, 1
	v_lshl_add_u64 v[4:5], s[44:45], 0, v[148:149]
	s_cbranch_scc1 .LBB0_575
	s_barrier
